# opt13 + G2 EpiResid epilogue regenerated by hand: residual loads two row groups ahead, SGPR-base addressing, counted vmcnt (no store drain per step)
# speedup vs baseline: 1.0209x; 1.0008x over previous
; __device__ __forceinline__ unsigned cvt_pk_bf16(float lo, float hi) { f32x2_t v = {lo, hi}; bf16x2_t b = __builtin_convertvector(v, bf16x2_t); return __builtin_bit_cast(unsigned, b); }
;     __device__ __forceinline__ void operator()(const Acc& acc, const Unit& u, int wr, int wc, int fr, int fq) const {
;         const int row0 = u.pm * BM + wr * 64 + fr, col0 = u.pn * BM + wc * 32 + 8 * fq;
; #pragma unroll
;         for (int ai = 0; ai < 2; ++ai)
; #pragma unroll
;             for (int m = 0; m < 4; ++m) {
;                 const int row = row0 + ai * HALF + m * 16; float sq = 0.f;
; #pragma unroll
;                 for (int bj = 0; bj < 2; ++bj) {
;                     const size_t off = (size_t)row * DM + col0 + bj * HALF;
;                     const f32x4 b0 = *(const f32x4*)(base + off), b1 = *(const f32x4*)(base + off + 4);
;                     const f32x4 x0 = b0 + acc[ai][bj][m][0] * alpha, x1 = b1 + acc[ai][bj][m][1] * alpha;
;                     __builtin_nontemporal_store(x0, (f32x4*)(out + off)); __builtin_nontemporal_store(x1, (f32x4*)(out + off + 4));
;                     sq += (x0[0] * x0[0] + x0[1] * x0[1]) + (x0[2] * x0[2] + x0[3] * x0[3]) + (x1[0] * x1[0] + x1[1] * x1[1]) + (x1[2] * x1[2] + x1[3] * x1[3]);
;                     if (xb) { u32x4 w; w.x = cvt_pk_bf16(x0[0], x0[1]); w.y = cvt_pk_bf16(x0[2], x0[3]); w.z = cvt_pk_bf16(x1[0], x1[1]); w.w = cvt_pk_bf16(x1[2], x1[3]); *(u32x4*)(xb + off) = w; }
;                 }
;                 sq += __shfl_xor(sq, 16); sq += __shfl_xor(sq, 32);
;                 if (fq == 0) unsafeAtomicAdd(ss + row, sq);
;             }
.LBB0_299:
	s_and_b64 vcc, exec, s[46:47]
	s_cbranch_vccz .Lg2_epi_old
	v_lshl_add_u32 v146, s31, 8, v154
	v_lshl_or_b32 v144, s33, 8, v156
	v_lshl_add_u32 v145, v146, 10, v144
	v_lshlrev_b32_e32 v144, 2, v145
	v_lshlrev_b32_e32 v145, 1, v145
	v_lshlrev_b32_e32 v146, 2, v146
	v_xor_b32_e32 v147, 16, v162
	v_lshlrev_b32_e32 v147, 2, v147
	v_xor_b32_e32 v148, 32, v162
	v_lshlrev_b32_e32 v148, 2, v148
	s_mov_b64 s[72:73], s[52:53]
	global_load_dwordx4 v[180:183], v144, s[72:73]
	global_load_dwordx4 v[184:187], v144, s[72:73] offset:16
	global_load_dwordx4 v[188:191], v144, s[72:73] offset:512
	global_load_dwordx4 v[192:195], v144, s[72:73] offset:528
	s_add_u32 s72, s52, 0x10000
	s_addc_u32 s73, s53, 0
	global_load_dwordx4 v[196:199], v144, s[72:73]
	global_load_dwordx4 v[200:203], v144, s[72:73] offset:16
	global_load_dwordx4 v[204:207], v144, s[72:73] offset:512
	global_load_dwordx4 v[208:211], v144, s[72:73] offset:528
	s_waitcnt vmcnt(4)
	v_fma_f32 v124, v124, 0.5, v180
	v_fma_f32 v125, v125, 0.5, v181
	v_fma_f32 v126, v126, 0.5, v182
	v_fma_f32 v127, v127, 0.5, v183
	v_fma_f32 v120, v120, 0.5, v184
	v_fma_f32 v121, v121, 0.5, v185
	v_fma_f32 v122, v122, 0.5, v186
	v_fma_f32 v123, v123, 0.5, v187
	v_fma_f32 v116, v116, 0.5, v188
	v_fma_f32 v117, v117, 0.5, v189
	v_fma_f32 v118, v118, 0.5, v190
	v_fma_f32 v119, v119, 0.5, v191
	v_fma_f32 v112, v112, 0.5, v192
	v_fma_f32 v113, v113, 0.5, v193
	v_fma_f32 v114, v114, 0.5, v194
	v_fma_f32 v115, v115, 0.5, v195
	s_add_u32 s72, s52, 0x20000
	s_addc_u32 s73, s53, 0
	global_load_dwordx4 v[212:215], v144, s[72:73]
	global_load_dwordx4 v[216:219], v144, s[72:73] offset:16
	global_load_dwordx4 v[220:223], v144, s[72:73] offset:512
	global_load_dwordx4 v[224:227], v144, s[72:73] offset:528
	s_mov_b64 s[74:75], s[90:91]
	global_store_dwordx4 v144, v[124:127], s[74:75] nt
	global_store_dwordx4 v144, v[120:123], s[74:75] offset:16 nt
	global_store_dwordx4 v144, v[116:119], s[74:75] offset:512 nt
	global_store_dwordx4 v144, v[112:115], s[74:75] offset:528 nt
	v_cvt_pk_bf16_f32 v232, v124, v125
	v_cvt_pk_bf16_f32 v233, v126, v127
	v_cvt_pk_bf16_f32 v234, v120, v121
	v_cvt_pk_bf16_f32 v235, v122, v123
	v_cvt_pk_bf16_f32 v236, v116, v117
	v_cvt_pk_bf16_f32 v237, v118, v119
	v_cvt_pk_bf16_f32 v238, v112, v113
	v_cvt_pk_bf16_f32 v239, v114, v115
	s_mov_b64 s[82:83], s[70:71]
	global_store_dwordx4 v145, v[232:235], s[82:83]
	global_store_dwordx4 v145, v[236:239], s[82:83] offset:256
	v_mul_f32_e32 v228, v125, v125
	v_fmac_f32_e32 v228, v124, v124
	v_mul_f32_e32 v229, v121, v121
	v_fmac_f32_e32 v229, v120, v120
	v_mul_f32_e32 v230, v117, v117
	v_fmac_f32_e32 v230, v116, v116
	v_mul_f32_e32 v231, v113, v113
	v_fmac_f32_e32 v231, v112, v112
	v_mul_f32_e32 v240, v127, v127
	v_fmac_f32_e32 v240, v126, v126
	v_mul_f32_e32 v241, v123, v123
	v_fmac_f32_e32 v241, v122, v122
	v_mul_f32_e32 v242, v119, v119
	v_fmac_f32_e32 v242, v118, v118
	v_mul_f32_e32 v243, v115, v115
	v_fmac_f32_e32 v243, v114, v114
	v_add_f32_e32 v228, v228, v240
	v_add_f32_e32 v229, v229, v241
	v_add_f32_e32 v230, v230, v242
	v_add_f32_e32 v231, v231, v243
	v_add_f32_e32 v228, v228, v229
	v_add_f32_e32 v230, v230, v231
	v_add_f32_e32 v228, v228, v230
	ds_bpermute_b32 v229, v147, v228
	s_waitcnt lgkmcnt(0)
	v_add_f32_e32 v228, v228, v229
	ds_bpermute_b32 v229, v148, v228
	s_waitcnt lgkmcnt(0)
	v_add_f32_e32 v228, v228, v229
	s_and_saveexec_b64 s[6:7], s[8:9]
	global_atomic_add_f32 v146, v228, s[44:45]
	s_mov_b64 exec, s[6:7]
	s_waitcnt vmcnt(11)
	v_fma_f32 v108, v108, 0.5, v196
	v_fma_f32 v109, v109, 0.5, v197
	v_fma_f32 v110, v110, 0.5, v198
	v_fma_f32 v111, v111, 0.5, v199
	v_fma_f32 v104, v104, 0.5, v200
	v_fma_f32 v105, v105, 0.5, v201
	v_fma_f32 v106, v106, 0.5, v202
	v_fma_f32 v107, v107, 0.5, v203
	v_fma_f32 v100, v100, 0.5, v204
	v_fma_f32 v101, v101, 0.5, v205
	v_fma_f32 v102, v102, 0.5, v206
	v_fma_f32 v103, v103, 0.5, v207
	v_fma_f32 v96, v96, 0.5, v208
	v_fma_f32 v97, v97, 0.5, v209
	v_fma_f32 v98, v98, 0.5, v210
	v_fma_f32 v99, v99, 0.5, v211
	s_add_u32 s72, s52, 0x30000
	s_addc_u32 s73, s53, 0
	global_load_dwordx4 v[180:183], v144, s[72:73]
	global_load_dwordx4 v[184:187], v144, s[72:73] offset:16
	global_load_dwordx4 v[188:191], v144, s[72:73] offset:512
	global_load_dwordx4 v[192:195], v144, s[72:73] offset:528
	s_add_u32 s74, s90, 0x10000
	s_addc_u32 s75, s91, 0
	global_store_dwordx4 v144, v[108:111], s[74:75] nt
	global_store_dwordx4 v144, v[104:107], s[74:75] offset:16 nt
	global_store_dwordx4 v144, v[100:103], s[74:75] offset:512 nt
	global_store_dwordx4 v144, v[96:99], s[74:75] offset:528 nt
	v_cvt_pk_bf16_f32 v232, v108, v109
	v_cvt_pk_bf16_f32 v233, v110, v111
	v_cvt_pk_bf16_f32 v234, v104, v105
	v_cvt_pk_bf16_f32 v235, v106, v107
	v_cvt_pk_bf16_f32 v236, v100, v101
	v_cvt_pk_bf16_f32 v237, v102, v103
	v_cvt_pk_bf16_f32 v238, v96, v97
	v_cvt_pk_bf16_f32 v239, v98, v99
	s_add_u32 s82, s70, 0x8000
	s_addc_u32 s83, s71, 0
	global_store_dwordx4 v145, v[232:235], s[82:83]
	global_store_dwordx4 v145, v[236:239], s[82:83] offset:256
	v_mul_f32_e32 v228, v109, v109
	v_fmac_f32_e32 v228, v108, v108
	v_mul_f32_e32 v229, v105, v105
	v_fmac_f32_e32 v229, v104, v104
	v_mul_f32_e32 v230, v101, v101
	v_fmac_f32_e32 v230, v100, v100
	v_mul_f32_e32 v231, v97, v97
	v_fmac_f32_e32 v231, v96, v96
	v_mul_f32_e32 v240, v111, v111
	v_fmac_f32_e32 v240, v110, v110
	v_mul_f32_e32 v241, v107, v107
	v_fmac_f32_e32 v241, v106, v106
	v_mul_f32_e32 v242, v103, v103
	v_fmac_f32_e32 v242, v102, v102
	v_mul_f32_e32 v243, v99, v99
	v_fmac_f32_e32 v243, v98, v98
	v_add_f32_e32 v228, v228, v240
	v_add_f32_e32 v229, v229, v241
	v_add_f32_e32 v230, v230, v242
	v_add_f32_e32 v231, v231, v243
	v_add_f32_e32 v228, v228, v229
	v_add_f32_e32 v230, v230, v231
	v_add_f32_e32 v228, v228, v230
	ds_bpermute_b32 v229, v147, v228
	s_waitcnt lgkmcnt(0)
; __device__ __forceinline__ unsigned cvt_pk_bf16(float lo, float hi) { f32x2_t v = {lo, hi}; bf16x2_t b = __builtin_convertvector(v, bf16x2_t); return __builtin_bit_cast(unsigned, b); }
;     __device__ __forceinline__ void operator()(const Acc& acc, const Unit& u, int wr, int wc, int fr, int fq) const {
;         const int row0 = u.pm * BM + wr * 64 + fr, col0 = u.pn * BM + wc * 32 + 8 * fq;
; #pragma unroll
;         for (int ai = 0; ai < 2; ++ai)
; #pragma unroll
;             for (int m = 0; m < 4; ++m) {
;                 const int row = row0 + ai * HALF + m * 16; float sq = 0.f;
; #pragma unroll
;                 for (int bj = 0; bj < 2; ++bj) {
;                     const size_t off = (size_t)row * DM + col0 + bj * HALF;
;                     const f32x4 b0 = *(const f32x4*)(base + off), b1 = *(const f32x4*)(base + off + 4);
;                     const f32x4 x0 = b0 + acc[ai][bj][m][0] * alpha, x1 = b1 + acc[ai][bj][m][1] * alpha;
;                     __builtin_nontemporal_store(x0, (f32x4*)(out + off)); __builtin_nontemporal_store(x1, (f32x4*)(out + off + 4));
;                     sq += (x0[0] * x0[0] + x0[1] * x0[1]) + (x0[2] * x0[2] + x0[3] * x0[3]) + (x1[0] * x1[0] + x1[1] * x1[1]) + (x1[2] * x1[2] + x1[3] * x1[3]);
;                     if (xb) { u32x4 w; w.x = cvt_pk_bf16(x0[0], x0[1]); w.y = cvt_pk_bf16(x0[2], x0[3]); w.z = cvt_pk_bf16(x1[0], x1[1]); w.w = cvt_pk_bf16(x1[2], x1[3]); *(u32x4*)(xb + off) = w; }
;                 }
;                 sq += __shfl_xor(sq, 16); sq += __shfl_xor(sq, 32);
;                 if (fq == 0) unsafeAtomicAdd(ss + row, sq);
;             }
	v_add_f32_e32 v228, v228, v229
	ds_bpermute_b32 v229, v148, v228
	s_waitcnt lgkmcnt(0)
	v_add_f32_e32 v228, v228, v229
	s_and_saveexec_b64 s[6:7], s[8:9]
	global_atomic_add_f32 v146, v228, s[44:45] offset:64
	s_mov_b64 exec, s[6:7]
	s_waitcnt vmcnt(18)
	v_fma_f32 v92, v92, 0.5, v212
	v_fma_f32 v93, v93, 0.5, v213
	v_fma_f32 v94, v94, 0.5, v214
	v_fma_f32 v95, v95, 0.5, v215
	v_fma_f32 v88, v88, 0.5, v216
	v_fma_f32 v89, v89, 0.5, v217
	v_fma_f32 v90, v90, 0.5, v218
	v_fma_f32 v91, v91, 0.5, v219
	v_fma_f32 v84, v84, 0.5, v220
	v_fma_f32 v85, v85, 0.5, v221
	v_fma_f32 v86, v86, 0.5, v222
	v_fma_f32 v87, v87, 0.5, v223
	v_fma_f32 v80, v80, 0.5, v224
	v_fma_f32 v81, v81, 0.5, v225
	v_fma_f32 v82, v82, 0.5, v226
	v_fma_f32 v83, v83, 0.5, v227
	s_add_u32 s72, s52, 0x80000
	s_addc_u32 s73, s53, 0
	global_load_dwordx4 v[196:199], v144, s[72:73]
	global_load_dwordx4 v[200:203], v144, s[72:73] offset:16
	global_load_dwordx4 v[204:207], v144, s[72:73] offset:512
	global_load_dwordx4 v[208:211], v144, s[72:73] offset:528
	s_add_u32 s74, s90, 0x20000
	s_addc_u32 s75, s91, 0
	global_store_dwordx4 v144, v[92:95], s[74:75] nt
	global_store_dwordx4 v144, v[88:91], s[74:75] offset:16 nt
	global_store_dwordx4 v144, v[84:87], s[74:75] offset:512 nt
	global_store_dwordx4 v144, v[80:83], s[74:75] offset:528 nt
	v_cvt_pk_bf16_f32 v232, v92, v93
	v_cvt_pk_bf16_f32 v233, v94, v95
	v_cvt_pk_bf16_f32 v234, v88, v89
	v_cvt_pk_bf16_f32 v235, v90, v91
	v_cvt_pk_bf16_f32 v236, v84, v85
	v_cvt_pk_bf16_f32 v237, v86, v87
	v_cvt_pk_bf16_f32 v238, v80, v81
	v_cvt_pk_bf16_f32 v239, v82, v83
	s_add_u32 s82, s70, 0x10000
	s_addc_u32 s83, s71, 0
	global_store_dwordx4 v145, v[232:235], s[82:83]
	global_store_dwordx4 v145, v[236:239], s[82:83] offset:256
	v_mul_f32_e32 v228, v93, v93
	v_fmac_f32_e32 v228, v92, v92
	v_mul_f32_e32 v229, v89, v89
	v_fmac_f32_e32 v229, v88, v88
	v_mul_f32_e32 v230, v85, v85
	v_fmac_f32_e32 v230, v84, v84
	v_mul_f32_e32 v231, v81, v81
	v_fmac_f32_e32 v231, v80, v80
	v_mul_f32_e32 v240, v95, v95
	v_fmac_f32_e32 v240, v94, v94
	v_mul_f32_e32 v241, v91, v91
	v_fmac_f32_e32 v241, v90, v90
	v_mul_f32_e32 v242, v87, v87
	v_fmac_f32_e32 v242, v86, v86
	v_mul_f32_e32 v243, v83, v83
	v_fmac_f32_e32 v243, v82, v82
	v_add_f32_e32 v228, v228, v240
	v_add_f32_e32 v229, v229, v241
	v_add_f32_e32 v230, v230, v242
	v_add_f32_e32 v231, v231, v243
	v_add_f32_e32 v228, v228, v229
	v_add_f32_e32 v230, v230, v231
	v_add_f32_e32 v228, v228, v230
	ds_bpermute_b32 v229, v147, v228
	s_waitcnt lgkmcnt(0)
	v_add_f32_e32 v228, v228, v229
	ds_bpermute_b32 v229, v148, v228
	s_waitcnt lgkmcnt(0)
	v_add_f32_e32 v228, v228, v229
	s_and_saveexec_b64 s[6:7], s[8:9]
	global_atomic_add_f32 v146, v228, s[44:45] offset:128
	s_mov_b64 exec, s[6:7]
	s_waitcnt vmcnt(18)
	v_fma_f32 v76, v76, 0.5, v180
	v_fma_f32 v77, v77, 0.5, v181
	v_fma_f32 v78, v78, 0.5, v182
	v_fma_f32 v79, v79, 0.5, v183
	v_fma_f32 v72, v72, 0.5, v184
	v_fma_f32 v73, v73, 0.5, v185
	v_fma_f32 v74, v74, 0.5, v186
	v_fma_f32 v75, v75, 0.5, v187
	v_fma_f32 v68, v68, 0.5, v188
	v_fma_f32 v69, v69, 0.5, v189
	v_fma_f32 v70, v70, 0.5, v190
	v_fma_f32 v71, v71, 0.5, v191
	v_fma_f32 v64, v64, 0.5, v192
	v_fma_f32 v65, v65, 0.5, v193
	v_fma_f32 v66, v66, 0.5, v194
	v_fma_f32 v67, v67, 0.5, v195
	s_add_u32 s72, s52, 0x90000
	s_addc_u32 s73, s53, 0
	global_load_dwordx4 v[212:215], v144, s[72:73]
	global_load_dwordx4 v[216:219], v144, s[72:73] offset:16
	global_load_dwordx4 v[220:223], v144, s[72:73] offset:512
	global_load_dwordx4 v[224:227], v144, s[72:73] offset:528
	s_add_u32 s74, s90, 0x30000
	s_addc_u32 s75, s91, 0
	global_store_dwordx4 v144, v[76:79], s[74:75] nt
	global_store_dwordx4 v144, v[72:75], s[74:75] offset:16 nt
	global_store_dwordx4 v144, v[68:71], s[74:75] offset:512 nt
	global_store_dwordx4 v144, v[64:67], s[74:75] offset:528 nt
	v_cvt_pk_bf16_f32 v232, v76, v77
	v_cvt_pk_bf16_f32 v233, v78, v79
	v_cvt_pk_bf16_f32 v234, v72, v73
	v_cvt_pk_bf16_f32 v235, v74, v75
	v_cvt_pk_bf16_f32 v236, v68, v69
	v_cvt_pk_bf16_f32 v237, v70, v71
	v_cvt_pk_bf16_f32 v238, v64, v65
	v_cvt_pk_bf16_f32 v239, v66, v67
	s_add_u32 s82, s70, 0x18000
	s_addc_u32 s83, s71, 0
	global_store_dwordx4 v145, v[232:235], s[82:83]
	global_store_dwordx4 v145, v[236:239], s[82:83] offset:256
	v_mul_f32_e32 v228, v77, v77
	v_fmac_f32_e32 v228, v76, v76
	v_mul_f32_e32 v229, v73, v73
	v_fmac_f32_e32 v229, v72, v72
	v_mul_f32_e32 v230, v69, v69
	v_fmac_f32_e32 v230, v68, v68
	v_mul_f32_e32 v231, v65, v65
	v_fmac_f32_e32 v231, v64, v64
	v_mul_f32_e32 v240, v79, v79
	v_fmac_f32_e32 v240, v78, v78
	v_mul_f32_e32 v241, v75, v75
	v_fmac_f32_e32 v241, v74, v74
	v_mul_f32_e32 v242, v71, v71
	v_fmac_f32_e32 v242, v70, v70
	v_mul_f32_e32 v243, v67, v67
	v_fmac_f32_e32 v243, v66, v66
	v_add_f32_e32 v228, v228, v240
	v_add_f32_e32 v229, v229, v241
	v_add_f32_e32 v230, v230, v242
	v_add_f32_e32 v231, v231, v243
	v_add_f32_e32 v228, v228, v229
	v_add_f32_e32 v230, v230, v231
	v_add_f32_e32 v228, v228, v230
	ds_bpermute_b32 v229, v147, v228
	s_waitcnt lgkmcnt(0)
	v_add_f32_e32 v228, v228, v229
	ds_bpermute_b32 v229, v148, v228
	s_waitcnt lgkmcnt(0)
	v_add_f32_e32 v228, v228, v229
	s_and_saveexec_b64 s[6:7], s[8:9]
	global_atomic_add_f32 v146, v228, s[44:45] offset:192
	s_mov_b64 exec, s[6:7]
	s_waitcnt vmcnt(18)
; __device__ __forceinline__ unsigned cvt_pk_bf16(float lo, float hi) { f32x2_t v = {lo, hi}; bf16x2_t b = __builtin_convertvector(v, bf16x2_t); return __builtin_bit_cast(unsigned, b); }
;     __device__ __forceinline__ void operator()(const Acc& acc, const Unit& u, int wr, int wc, int fr, int fq) const {
;         const int row0 = u.pm * BM + wr * 64 + fr, col0 = u.pn * BM + wc * 32 + 8 * fq;
; #pragma unroll
;         for (int ai = 0; ai < 2; ++ai)
; #pragma unroll
;             for (int m = 0; m < 4; ++m) {
;                 const int row = row0 + ai * HALF + m * 16; float sq = 0.f;
; #pragma unroll
;                 for (int bj = 0; bj < 2; ++bj) {
;                     const size_t off = (size_t)row * DM + col0 + bj * HALF;
;                     const f32x4 b0 = *(const f32x4*)(base + off), b1 = *(const f32x4*)(base + off + 4);
;                     const f32x4 x0 = b0 + acc[ai][bj][m][0] * alpha, x1 = b1 + acc[ai][bj][m][1] * alpha;
;                     __builtin_nontemporal_store(x0, (f32x4*)(out + off)); __builtin_nontemporal_store(x1, (f32x4*)(out + off + 4));
;                     sq += (x0[0] * x0[0] + x0[1] * x0[1]) + (x0[2] * x0[2] + x0[3] * x0[3]) + (x1[0] * x1[0] + x1[1] * x1[1]) + (x1[2] * x1[2] + x1[3] * x1[3]);
;                     if (xb) { u32x4 w; w.x = cvt_pk_bf16(x0[0], x0[1]); w.y = cvt_pk_bf16(x0[2], x0[3]); w.z = cvt_pk_bf16(x1[0], x1[1]); w.w = cvt_pk_bf16(x1[2], x1[3]); *(u32x4*)(xb + off) = w; }
;                 }
;                 sq += __shfl_xor(sq, 16); sq += __shfl_xor(sq, 32);
;                 if (fq == 0) unsafeAtomicAdd(ss + row, sq);
;             }
	v_fma_f32 v60, v60, 0.5, v196
	v_fma_f32 v61, v61, 0.5, v197
	v_fma_f32 v62, v62, 0.5, v198
	v_fma_f32 v63, v63, 0.5, v199
	v_fma_f32 v56, v56, 0.5, v200
	v_fma_f32 v57, v57, 0.5, v201
	v_fma_f32 v58, v58, 0.5, v202
	v_fma_f32 v59, v59, 0.5, v203
	v_fma_f32 v52, v52, 0.5, v204
	v_fma_f32 v53, v53, 0.5, v205
	v_fma_f32 v54, v54, 0.5, v206
	v_fma_f32 v55, v55, 0.5, v207
	v_fma_f32 v48, v48, 0.5, v208
	v_fma_f32 v49, v49, 0.5, v209
	v_fma_f32 v50, v50, 0.5, v210
	v_fma_f32 v51, v51, 0.5, v211
	s_add_u32 s72, s52, 0xa0000
	s_addc_u32 s73, s53, 0
	global_load_dwordx4 v[180:183], v144, s[72:73]
	global_load_dwordx4 v[184:187], v144, s[72:73] offset:16
	global_load_dwordx4 v[188:191], v144, s[72:73] offset:512
	global_load_dwordx4 v[192:195], v144, s[72:73] offset:528
	s_add_u32 s74, s90, 0x80000
	s_addc_u32 s75, s91, 0
	global_store_dwordx4 v144, v[60:63], s[74:75] nt
	global_store_dwordx4 v144, v[56:59], s[74:75] offset:16 nt
	global_store_dwordx4 v144, v[52:55], s[74:75] offset:512 nt
	global_store_dwordx4 v144, v[48:51], s[74:75] offset:528 nt
	v_cvt_pk_bf16_f32 v232, v60, v61
	v_cvt_pk_bf16_f32 v233, v62, v63
	v_cvt_pk_bf16_f32 v234, v56, v57
	v_cvt_pk_bf16_f32 v235, v58, v59
	v_cvt_pk_bf16_f32 v236, v52, v53
	v_cvt_pk_bf16_f32 v237, v54, v55
	v_cvt_pk_bf16_f32 v238, v48, v49
	v_cvt_pk_bf16_f32 v239, v50, v51
	s_add_u32 s82, s70, 0x40000
	s_addc_u32 s83, s71, 0
	global_store_dwordx4 v145, v[232:235], s[82:83]
	global_store_dwordx4 v145, v[236:239], s[82:83] offset:256
	v_mul_f32_e32 v228, v61, v61
	v_fmac_f32_e32 v228, v60, v60
	v_mul_f32_e32 v229, v57, v57
	v_fmac_f32_e32 v229, v56, v56
	v_mul_f32_e32 v230, v53, v53
	v_fmac_f32_e32 v230, v52, v52
	v_mul_f32_e32 v231, v49, v49
	v_fmac_f32_e32 v231, v48, v48
	v_mul_f32_e32 v240, v63, v63
	v_fmac_f32_e32 v240, v62, v62
	v_mul_f32_e32 v241, v59, v59
	v_fmac_f32_e32 v241, v58, v58
	v_mul_f32_e32 v242, v55, v55
	v_fmac_f32_e32 v242, v54, v54
	v_mul_f32_e32 v243, v51, v51
	v_fmac_f32_e32 v243, v50, v50
	v_add_f32_e32 v228, v228, v240
	v_add_f32_e32 v229, v229, v241
	v_add_f32_e32 v230, v230, v242
	v_add_f32_e32 v231, v231, v243
	v_add_f32_e32 v228, v228, v229
	v_add_f32_e32 v230, v230, v231
	v_add_f32_e32 v228, v228, v230
	ds_bpermute_b32 v229, v147, v228
	s_waitcnt lgkmcnt(0)
	v_add_f32_e32 v228, v228, v229
	ds_bpermute_b32 v229, v148, v228
	s_waitcnt lgkmcnt(0)
	v_add_f32_e32 v228, v228, v229
	s_and_saveexec_b64 s[6:7], s[8:9]
	global_atomic_add_f32 v146, v228, s[44:45] offset:512
	s_mov_b64 exec, s[6:7]
	s_waitcnt vmcnt(18)
	v_fma_f32 v44, v44, 0.5, v212
	v_fma_f32 v45, v45, 0.5, v213
	v_fma_f32 v46, v46, 0.5, v214
	v_fma_f32 v47, v47, 0.5, v215
	v_fma_f32 v40, v40, 0.5, v216
	v_fma_f32 v41, v41, 0.5, v217
	v_fma_f32 v42, v42, 0.5, v218
	v_fma_f32 v43, v43, 0.5, v219
	v_fma_f32 v36, v36, 0.5, v220
	v_fma_f32 v37, v37, 0.5, v221
	v_fma_f32 v38, v38, 0.5, v222
	v_fma_f32 v39, v39, 0.5, v223
	v_fma_f32 v32, v32, 0.5, v224
	v_fma_f32 v33, v33, 0.5, v225
	v_fma_f32 v34, v34, 0.5, v226
	v_fma_f32 v35, v35, 0.5, v227
	s_add_u32 s72, s52, 0xb0000
	s_addc_u32 s73, s53, 0
	global_load_dwordx4 v[196:199], v144, s[72:73]
	global_load_dwordx4 v[200:203], v144, s[72:73] offset:16
	global_load_dwordx4 v[204:207], v144, s[72:73] offset:512
	global_load_dwordx4 v[208:211], v144, s[72:73] offset:528
	s_add_u32 s74, s90, 0x90000
	s_addc_u32 s75, s91, 0
	global_store_dwordx4 v144, v[44:47], s[74:75] nt
	global_store_dwordx4 v144, v[40:43], s[74:75] offset:16 nt
	global_store_dwordx4 v144, v[36:39], s[74:75] offset:512 nt
	global_store_dwordx4 v144, v[32:35], s[74:75] offset:528 nt
	v_cvt_pk_bf16_f32 v232, v44, v45
	v_cvt_pk_bf16_f32 v233, v46, v47
	v_cvt_pk_bf16_f32 v234, v40, v41
	v_cvt_pk_bf16_f32 v235, v42, v43
	v_cvt_pk_bf16_f32 v236, v36, v37
	v_cvt_pk_bf16_f32 v237, v38, v39
	v_cvt_pk_bf16_f32 v238, v32, v33
	v_cvt_pk_bf16_f32 v239, v34, v35
	s_add_u32 s82, s70, 0x48000
	s_addc_u32 s83, s71, 0
	global_store_dwordx4 v145, v[232:235], s[82:83]
	global_store_dwordx4 v145, v[236:239], s[82:83] offset:256
	v_mul_f32_e32 v228, v45, v45
	v_fmac_f32_e32 v228, v44, v44
	v_mul_f32_e32 v229, v41, v41
	v_fmac_f32_e32 v229, v40, v40
	v_mul_f32_e32 v230, v37, v37
	v_fmac_f32_e32 v230, v36, v36
	v_mul_f32_e32 v231, v33, v33
	v_fmac_f32_e32 v231, v32, v32
	v_mul_f32_e32 v240, v47, v47
	v_fmac_f32_e32 v240, v46, v46
	v_mul_f32_e32 v241, v43, v43
	v_fmac_f32_e32 v241, v42, v42
	v_mul_f32_e32 v242, v39, v39
	v_fmac_f32_e32 v242, v38, v38
	v_mul_f32_e32 v243, v35, v35
	v_fmac_f32_e32 v243, v34, v34
	v_add_f32_e32 v228, v228, v240
	v_add_f32_e32 v229, v229, v241
	v_add_f32_e32 v230, v230, v242
	v_add_f32_e32 v231, v231, v243
	v_add_f32_e32 v228, v228, v229
	v_add_f32_e32 v230, v230, v231
	v_add_f32_e32 v228, v228, v230
	ds_bpermute_b32 v229, v147, v228
	s_waitcnt lgkmcnt(0)
; __device__ __forceinline__ unsigned cvt_pk_bf16(float lo, float hi) { f32x2_t v = {lo, hi}; bf16x2_t b = __builtin_convertvector(v, bf16x2_t); return __builtin_bit_cast(unsigned, b); }
;     __device__ __forceinline__ void operator()(const Acc& acc, const Unit& u, int wr, int wc, int fr, int fq) const {
;         const int row0 = u.pm * BM + wr * 64 + fr, col0 = u.pn * BM + wc * 32 + 8 * fq;
; #pragma unroll
;         for (int ai = 0; ai < 2; ++ai)
; #pragma unroll
;             for (int m = 0; m < 4; ++m) {
;                 const int row = row0 + ai * HALF + m * 16; float sq = 0.f;
; #pragma unroll
;                 for (int bj = 0; bj < 2; ++bj) {
;                     const size_t off = (size_t)row * DM + col0 + bj * HALF;
;                     const f32x4 b0 = *(const f32x4*)(base + off), b1 = *(const f32x4*)(base + off + 4);
;                     const f32x4 x0 = b0 + acc[ai][bj][m][0] * alpha, x1 = b1 + acc[ai][bj][m][1] * alpha;
;                     __builtin_nontemporal_store(x0, (f32x4*)(out + off)); __builtin_nontemporal_store(x1, (f32x4*)(out + off + 4));
;                     sq += (x0[0] * x0[0] + x0[1] * x0[1]) + (x0[2] * x0[2] + x0[3] * x0[3]) + (x1[0] * x1[0] + x1[1] * x1[1]) + (x1[2] * x1[2] + x1[3] * x1[3]);
;                     if (xb) { u32x4 w; w.x = cvt_pk_bf16(x0[0], x0[1]); w.y = cvt_pk_bf16(x0[2], x0[3]); w.z = cvt_pk_bf16(x1[0], x1[1]); w.w = cvt_pk_bf16(x1[2], x1[3]); *(u32x4*)(xb + off) = w; }
;                 }
;                 sq += __shfl_xor(sq, 16); sq += __shfl_xor(sq, 32);
;                 if (fq == 0) unsafeAtomicAdd(ss + row, sq);
;             }
	v_add_f32_e32 v228, v228, v229
	ds_bpermute_b32 v229, v148, v228
	s_waitcnt lgkmcnt(0)
	v_add_f32_e32 v228, v228, v229
	s_and_saveexec_b64 s[6:7], s[8:9]
	global_atomic_add_f32 v146, v228, s[44:45] offset:576
	s_mov_b64 exec, s[6:7]
	s_waitcnt vmcnt(18)
	v_fma_f32 v28, v28, 0.5, v180
	v_fma_f32 v29, v29, 0.5, v181
	v_fma_f32 v30, v30, 0.5, v182
	v_fma_f32 v31, v31, 0.5, v183
	v_fma_f32 v24, v24, 0.5, v184
	v_fma_f32 v25, v25, 0.5, v185
	v_fma_f32 v26, v26, 0.5, v186
	v_fma_f32 v27, v27, 0.5, v187
	v_fma_f32 v20, v20, 0.5, v188
	v_fma_f32 v21, v21, 0.5, v189
	v_fma_f32 v22, v22, 0.5, v190
	v_fma_f32 v23, v23, 0.5, v191
	v_fma_f32 v16, v16, 0.5, v192
	v_fma_f32 v17, v17, 0.5, v193
	v_fma_f32 v18, v18, 0.5, v194
	v_fma_f32 v19, v19, 0.5, v195
	s_add_u32 s74, s90, 0xa0000
	s_addc_u32 s75, s91, 0
	global_store_dwordx4 v144, v[28:31], s[74:75] nt
	global_store_dwordx4 v144, v[24:27], s[74:75] offset:16 nt
	global_store_dwordx4 v144, v[20:23], s[74:75] offset:512 nt
	global_store_dwordx4 v144, v[16:19], s[74:75] offset:528 nt
	v_cvt_pk_bf16_f32 v232, v28, v29
	v_cvt_pk_bf16_f32 v233, v30, v31
	v_cvt_pk_bf16_f32 v234, v24, v25
	v_cvt_pk_bf16_f32 v235, v26, v27
	v_cvt_pk_bf16_f32 v236, v20, v21
	v_cvt_pk_bf16_f32 v237, v22, v23
	v_cvt_pk_bf16_f32 v238, v16, v17
	v_cvt_pk_bf16_f32 v239, v18, v19
	s_add_u32 s82, s70, 0x50000
	s_addc_u32 s83, s71, 0
	global_store_dwordx4 v145, v[232:235], s[82:83]
	global_store_dwordx4 v145, v[236:239], s[82:83] offset:256
	v_mul_f32_e32 v228, v29, v29
	v_fmac_f32_e32 v228, v28, v28
	v_mul_f32_e32 v229, v25, v25
	v_fmac_f32_e32 v229, v24, v24
	v_mul_f32_e32 v230, v21, v21
	v_fmac_f32_e32 v230, v20, v20
	v_mul_f32_e32 v231, v17, v17
	v_fmac_f32_e32 v231, v16, v16
	v_mul_f32_e32 v240, v31, v31
	v_fmac_f32_e32 v240, v30, v30
	v_mul_f32_e32 v241, v27, v27
	v_fmac_f32_e32 v241, v26, v26
	v_mul_f32_e32 v242, v23, v23
	v_fmac_f32_e32 v242, v22, v22
	v_mul_f32_e32 v243, v19, v19
	v_fmac_f32_e32 v243, v18, v18
	v_add_f32_e32 v228, v228, v240
	v_add_f32_e32 v229, v229, v241
	v_add_f32_e32 v230, v230, v242
	v_add_f32_e32 v231, v231, v243
	v_add_f32_e32 v228, v228, v229
	v_add_f32_e32 v230, v230, v231
	v_add_f32_e32 v228, v228, v230
	ds_bpermute_b32 v229, v147, v228
	s_waitcnt lgkmcnt(0)
	v_add_f32_e32 v228, v228, v229
	ds_bpermute_b32 v229, v148, v228
	s_waitcnt lgkmcnt(0)
	v_add_f32_e32 v228, v228, v229
	s_and_saveexec_b64 s[6:7], s[8:9]
	global_atomic_add_f32 v146, v228, s[44:45] offset:640
	s_mov_b64 exec, s[6:7]
	s_waitcnt vmcnt(14)
	v_fma_f32 v12, v12, 0.5, v196
	v_fma_f32 v13, v13, 0.5, v197
	v_fma_f32 v14, v14, 0.5, v198
	v_fma_f32 v15, v15, 0.5, v199
	v_fma_f32 v8, v8, 0.5, v200
	v_fma_f32 v9, v9, 0.5, v201
	v_fma_f32 v10, v10, 0.5, v202
	v_fma_f32 v11, v11, 0.5, v203
	v_fma_f32 v4, v4, 0.5, v204
	v_fma_f32 v5, v5, 0.5, v205
	v_fma_f32 v6, v6, 0.5, v206
	v_fma_f32 v7, v7, 0.5, v207
	v_fma_f32 v0, v0, 0.5, v208
	v_fma_f32 v1, v1, 0.5, v209
	v_fma_f32 v2, v2, 0.5, v210
	v_fma_f32 v3, v3, 0.5, v211
	s_add_u32 s74, s90, 0xb0000
	s_addc_u32 s75, s91, 0
	global_store_dwordx4 v144, v[12:15], s[74:75] nt
	global_store_dwordx4 v144, v[8:11], s[74:75] offset:16 nt
	global_store_dwordx4 v144, v[4:7], s[74:75] offset:512 nt
	global_store_dwordx4 v144, v[0:3], s[74:75] offset:528 nt
	v_cvt_pk_bf16_f32 v232, v12, v13
	v_cvt_pk_bf16_f32 v233, v14, v15
	v_cvt_pk_bf16_f32 v234, v8, v9
	v_cvt_pk_bf16_f32 v235, v10, v11
	v_cvt_pk_bf16_f32 v236, v4, v5
	v_cvt_pk_bf16_f32 v237, v6, v7
	v_cvt_pk_bf16_f32 v238, v0, v1
	v_cvt_pk_bf16_f32 v239, v2, v3
	s_add_u32 s82, s70, 0x58000
	s_addc_u32 s83, s71, 0
	global_store_dwordx4 v145, v[232:235], s[82:83]
	global_store_dwordx4 v145, v[236:239], s[82:83] offset:256
	v_mul_f32_e32 v228, v13, v13
	v_fmac_f32_e32 v228, v12, v12
	v_mul_f32_e32 v229, v9, v9
	v_fmac_f32_e32 v229, v8, v8
	v_mul_f32_e32 v230, v5, v5
	v_fmac_f32_e32 v230, v4, v4
	v_mul_f32_e32 v231, v1, v1
	v_fmac_f32_e32 v231, v0, v0
	v_mul_f32_e32 v240, v15, v15
	v_fmac_f32_e32 v240, v14, v14
	v_mul_f32_e32 v241, v11, v11
	v_fmac_f32_e32 v241, v10, v10
	v_mul_f32_e32 v242, v7, v7
	v_fmac_f32_e32 v242, v6, v6
	v_mul_f32_e32 v243, v3, v3
	v_fmac_f32_e32 v243, v2, v2
	v_add_f32_e32 v228, v228, v240
	v_add_f32_e32 v229, v229, v241
	v_add_f32_e32 v230, v230, v242
	v_add_f32_e32 v231, v231, v243
	v_add_f32_e32 v228, v228, v229
	v_add_f32_e32 v230, v230, v231
	v_add_f32_e32 v228, v228, v230
	ds_bpermute_b32 v229, v147, v228
	s_waitcnt lgkmcnt(0)
	v_add_f32_e32 v228, v228, v229
	ds_bpermute_b32 v229, v148, v228
	s_waitcnt lgkmcnt(0)
	v_add_f32_e32 v228, v228, v229
	s_and_saveexec_b64 s[6:7], s[8:9]
	global_atomic_add_f32 v146, v228, s[44:45] offset:704
	s_mov_b64 exec, s[6:7]
	s_branch .Lg2_epi_done

; #define PG8_BAR __builtin_amdgcn_s_barrier()
; template <class Epi>
; __device__ __forceinline__ void gemm_phase(LAS unsigned char* lds, const Gemm g, const StaticOrder& S, const Epi& E) {
;     ...
;         if (!has_next) break;
; #pragma unroll
;         for (int a = 0; a < 2; ++a)
; #pragma unroll
;             for (int b = 0; b < 2; ++b)
; #pragma unroll
;                 for (int m = 0; m < 4; ++m)
; #pragma unroll
;                     for (int n = 0; n < 2; ++n) acc[a][b][m][n] = (f32x4){0.f, 0.f, 0.f, 0.f};
;         cur = nxt; cA = nA; cB = nB; ++ui;
;         if (wr == 1) PG8_BAR;
.Lg2_epi_done:
	s_and_b64 vcc, exec, s[10:11]
	s_mov_b64 s[6:7], -1
	s_cbranch_vccnz .LBB0_284
	s_andn2_b64 vcc, exec, s[2:3]
	s_cbranch_vccnz .LBB0_283
	s_barrier
	s_branch .LBB0_283

.LBB0_862:
	v_max_f32_e32 v34, v16, v17
	v_max_f32_e32 v37, v0, v1
	v_max3_f32 v34, v34, v18, v19
	v_max3_f32 v37, v37, v2, v3
	v_max3_f32 v34, v34, v20, v21
	v_max3_f32 v37, v37, v4, v5
	v_max3_f32 v34, v34, v22, v23
	v_max3_f32 v37, v37, v6, v7
	v_max3_f32 v34, v34, v24, v25
	v_max3_f32 v37, v37, v8, v9
	v_max3_f32 v34, v34, v26, v27
	v_max3_f32 v37, v37, v10, v11
	v_max3_f32 v34, v34, v28, v29
	v_max3_f32 v37, v37, v12, v13
	v_max3_f32 v34, v34, v30, v31
	v_max3_f32 v37, v37, v14, v15
	v_add_f32_e32 v34, v35, v34
	v_add_f32_e32 v37, v36, v37
	v_max_f32_e32 v34, v34, v37
	v_mov_b32_e32 v37, v34
	s_nop 1
	v_permlane32_swap_b32_e32 v34, v37
	v_max_f32_e32 v34, v34, v37
	v_add_f32_e32 v37, 0x7f800000, v34
	v_cmp_gt_f32_e32 vcc, s18, v37
	s_cmp_lg_u64 vcc, exec
	s_cselect_b64 s[82:83], -1, 0
	s_cmp_eq_u64 vcc, exec
	s_cbranch_scc1 .LBB0_864
	v_max_f32_e32 v34, v34, v34
	v_max_f32_e32 v112, 0xff800000, v34
	v_sub_f32_e32 v51, v112, v35
	v_sub_f32_e32 v52, v112, v36
	v_sub_f32_e32 v16, v16, v51
	v_sub_f32_e32 v0, v0, v52
	v_exp_f32_e32 v34, v16
	v_exp_f32_e32 v35, v0
	v_sub_f32_e32 v0, v17, v51
	v_sub_f32_e32 v1, v1, v52
	v_exp_f32_e32 v0, v0
	v_exp_f32_e32 v1, v1
	v_sub_f32_e32 v16, v18, v51
	v_sub_f32_e32 v2, v2, v52
	v_exp_f32_e32 v36, v16
	v_exp_f32_e32 v37, v2
	v_sub_f32_e32 v2, v19, v51
	v_sub_f32_e32 v3, v3, v52
	v_exp_f32_e32 v2, v2
	v_exp_f32_e32 v3, v3
	v_sub_f32_e32 v18, v20, v51
	v_sub_f32_e32 v4, v4, v52
	v_add_f32_e32 v16, 0, v34
	v_add_f32_e32 v17, 0, v35
	v_exp_f32_e32 v38, v18
	v_exp_f32_e32 v39, v4
	v_sub_f32_e32 v4, v21, v51
	v_sub_f32_e32 v5, v5, v52
	v_add_f32_e32 v16, v0, v16
	v_add_f32_e32 v17, v1, v17
	v_exp_f32_e32 v4, v4
	v_exp_f32_e32 v5, v5
	v_sub_f32_e32 v18, v22, v51
	v_sub_f32_e32 v6, v6, v52
	v_add_f32_e32 v16, v36, v16
	v_add_f32_e32 v17, v37, v17
	v_exp_f32_e32 v40, v18
	v_exp_f32_e32 v41, v6
	v_sub_f32_e32 v6, v23, v51
	v_sub_f32_e32 v7, v7, v52
	v_add_f32_e32 v16, v2, v16
	v_add_f32_e32 v17, v3, v17
	v_exp_f32_e32 v6, v6
	v_exp_f32_e32 v7, v7
	v_sub_f32_e32 v18, v24, v51
	v_sub_f32_e32 v8, v8, v52
	v_exp_f32_e32 v42, v18
	v_exp_f32_e32 v43, v8
	v_sub_f32_e32 v8, v25, v51
	v_sub_f32_e32 v9, v9, v52
	v_add_f32_e32 v16, v38, v16
	v_add_f32_e32 v17, v39, v17
	v_exp_f32_e32 v8, v8
	v_exp_f32_e32 v9, v9
	v_sub_f32_e32 v18, v26, v51
	v_sub_f32_e32 v10, v10, v52
	v_add_f32_e32 v16, v4, v16
	v_add_f32_e32 v17, v5, v17
	v_exp_f32_e32 v44, v18
	v_exp_f32_e32 v45, v10
	v_sub_f32_e32 v10, v27, v51
	v_sub_f32_e32 v11, v11, v52
	v_add_f32_e32 v16, v40, v16
	v_add_f32_e32 v17, v41, v17
	v_exp_f32_e32 v10, v10
	v_exp_f32_e32 v11, v11
	v_sub_f32_e32 v18, v28, v51
	v_sub_f32_e32 v12, v12, v52
	v_add_f32_e32 v16, v6, v16
	v_add_f32_e32 v17, v7, v17
	v_sub_f32_e32 v50, 0xff800000, v112
	v_exp_f32_e32 v46, v18
	v_exp_f32_e32 v47, v12
	v_sub_f32_e32 v12, v29, v51
	v_sub_f32_e32 v13, v13, v52
	v_sub_f32_e32 v18, v30, v51
	v_add_f32_e32 v16, v42, v16
	v_add_f32_e32 v17, v43, v17
	v_exp_f32_e32 v12, v12
	v_exp_f32_e32 v13, v13
	v_exp_f32_e32 v48, v18
	v_sub_f32_e32 v14, v14, v52
	v_add_f32_e32 v16, v8, v16
	v_add_f32_e32 v17, v9, v17
	v_exp_f32_e32 v18, v50
	v_exp_f32_e32 v49, v14
	v_sub_f32_e32 v14, v31, v51
	v_sub_f32_e32 v15, v15, v52
	v_add_f32_e32 v16, v44, v16
	v_add_f32_e32 v17, v45, v17
	v_exp_f32_e32 v14, v14
	v_exp_f32_e32 v15, v15
	v_add_f32_e32 v16, v10, v16
	v_add_f32_e32 v17, v11, v17
	v_cmp_neq_f32_e32 vcc, 1.0, v18
	v_add_f32_e32 v16, v46, v16
	v_add_f32_e32 v17, v47, v17
	s_cmp_lg_u64 vcc, 0
	v_add_f32_e32 v16, v12, v16
	v_add_f32_e32 v17, v13, v17
	v_mul_f32_e32 v19, 0, v18
	v_add_f32_e32 v16, v48, v16
	v_add_f32_e32 v17, v49, v17
	s_cselect_b64 vcc, -1, 0
	v_add_f32_e32 v16, v14, v16
	v_add_f32_e32 v17, v15, v17
	v_cvt_pk_bf16_f32 v144, v34, v0
	v_add_f32_e32 v193, v16, v17
	v_cndmask_b32_e32 v16, 0, v19, vcc
	v_fmac_f32_e32 v193, 0, v18
	v_mov_b32_e32 v17, v16
	v_mov_b32_e32 v18, v16
	v_mov_b32_e32 v19, v16
	v_mov_b32_e32 v20, v16
	v_mov_b32_e32 v21, v16
	v_mov_b32_e32 v22, v16
	v_mov_b32_e32 v23, v16
	v_mov_b32_e32 v24, v16
	v_mov_b32_e32 v25, v16
	v_mov_b32_e32 v26, v16
	v_mov_b32_e32 v27, v16
	v_mov_b32_e32 v28, v16
	v_mov_b32_e32 v29, v16
	v_mov_b32_e32 v30, v16
	v_mov_b32_e32 v31, v16
	v_cvt_pk_bf16_f32 v145, v36, v2
	v_cvt_pk_bf16_f32 v146, v38, v4
	v_cvt_pk_bf16_f32 v147, v40, v6
	v_cvt_pk_bf16_f32 v148, v42, v8
	v_cvt_pk_bf16_f32 v149, v44, v10
	v_cvt_pk_bf16_f32 v150, v46, v12
	v_cvt_pk_bf16_f32 v151, v48, v14
	v_cvt_pk_bf16_f32 v152, v35, v1
	v_cvt_pk_bf16_f32 v153, v37, v3
	v_cvt_pk_bf16_f32 v154, v39, v5
	v_cvt_pk_bf16_f32 v155, v41, v7
	v_cvt_pk_bf16_f32 v156, v43, v9
	v_cvt_pk_bf16_f32 v157, v45, v11
	v_cvt_pk_bf16_f32 v158, v47, v13
	v_cvt_pk_bf16_f32 v159, v49, v15
	s_branch .LBB0_865
